# scan loader: weight-copy row loads issued before the next chunk preparation, preparation waits rebased
# speedup vs baseline: 1.0035x; 1.0035x over previous
.LBB0_585:
	s_add_i32 s6, s55, 0x8000
	s_cmp_gt_i32 s6, 0x9fff
	s_cselect_b64 s[8:9], -1, 0
	s_or_b64 s[8:9], s[90:91], s[8:9]
	s_and_b64 vcc, exec, s[8:9]
	s_cbranch_vccnz .Ltr_issue_done
	s_cmpk_gt_i32 s6, 0x3fff
	s_mov_b64 vcc, -1
	s_cbranch_scc0 .LBB0_608
	s_cmpk_gt_u32 s6, 0x7fff
	s_cbranch_scc0 .LBB0_605
	s_and_b32 s87, s6, 0x7ff
	s_lshr_b32 s7, s55, 11
	s_cmp_eq_u32 s7, 2
	s_cselect_b32 s10, s33, 0xd8
	s_cmp_lg_u32 s7, 1
	s_cselect_b32 s10, s10, 0x108
	s_cmpk_gt_u32 s55, 0x7ff
	s_cselect_b32 s10, s10, 0x100
	v_readlane_b32 s18, v251, 13
	v_readlane_b32 s19, v251, 14
	s_add_u32 s10, s18, s10
	s_addc_u32 s11, s19, 0
	s_lshl_b32 s82, s7, 3
	s_load_dwordx2 s[18:19], s[10:11], 0x0
	s_lshl_b64 s[10:11], s[82:83], 20
	s_add_u32 s10, s10, 0xbe00000
	s_addc_u32 s11, s11, 0
	s_cmp_lg_u32 s7, 3
	s_cselect_b32 s10, s10, 0xd600000
	s_cselect_b32 s7, s11, 0
	s_add_u32 s10, s60, s10
	s_addc_u32 s11, s61, s7
	s_mov_b64 vcc, 0

.Ltr_issue_done:
	s_mov_b64 s[98:99], s[8:9]
	s_and_b64 s[100:101], exec, s[98:99]
	s_cbranch_scc0 .Ltr_w1_far
	s_waitcnt vmcnt(6)
	s_branch .Ltr_w1_done
.Ltr_w1_far:
	s_waitcnt vmcnt(38)
.Ltr_w1_done:
	v_lshlrev_b32_e32 v82, 16, v142
	v_and_b32_e32 v83, 0xffff0000, v142
	v_lshlrev_b32_e32 v78, 16, v143
	v_and_b32_e32 v79, 0xffff0000, v143
	v_pk_mul_f32 v[84:85], v[38:39], v[78:79]
	v_pk_mul_f32 v[86:87], v[36:37], v[82:83]
	v_pk_mul_f32 v[230:231], v[84:85], v[84:85]
	v_pk_mul_f32 v[232:233], v[86:87], v[86:87]
	s_and_b64 s[100:101], exec, s[98:99]
	s_cbranch_scc0 .Ltr_w2_far
	s_waitcnt vmcnt(4)
	s_branch .Ltr_w2_done
.Ltr_w2_far:
	s_waitcnt vmcnt(36)

.LBB0_593:
	s_or_b64 exec, exec, s[8:9]
	s_and_b64 s[100:101], exec, s[98:99]
	s_cbranch_scc0 .Ltr_w3_far
	s_waitcnt vmcnt(2)
	s_branch .Ltr_w3_done
.Ltr_w3_far:
	s_waitcnt vmcnt(34)
.Ltr_w3_done:
	v_lshlrev_b32_e32 v82, 16, v152
	v_and_b32_e32 v83, 0xffff0000, v152
	v_lshlrev_b32_e32 v78, 16, v153
	v_and_b32_e32 v79, 0xffff0000, v153
	v_pk_mul_f32 v[84:85], v[38:39], v[78:79]
	v_pk_mul_f32 v[86:87], v[36:37], v[82:83]
	v_pk_mul_f32 v[230:231], v[84:85], v[84:85]
	v_pk_mul_f32 v[232:233], v[86:87], v[86:87]
	s_and_b64 s[100:101], exec, s[98:99]
	s_cbranch_scc0 .Ltr_w4_far
	s_waitcnt vmcnt(0)
	s_branch .Ltr_w4_done
.Ltr_w4_far:
	s_waitcnt vmcnt(32)

.LBB0_611:
	s_xor_b64 s[8:9], s[98:99], -1
	s_add_i32 s57, s57, 1
	s_cmp_gt_u32 s57, 61
	s_cbranch_scc1 .LBB0_621
	v_lshl_add_u64 v[72:73], s[60:61], 0, v[160:161]
	v_add_co_u32_e32 v64, vcc, 0x1a060000, v72
	v_mov_b32_e32 v146, 0
	s_nop 0
	v_addc_co_u32_e32 v65, vcc, 0, v73, vcc
	v_add_co_u32_e32 v66, vcc, 0x1c060000, v72
	v_mov_b32_e32 v147, v0
	s_nop 0
	v_addc_co_u32_e32 v67, vcc, 0, v73, vcc
	global_load_dwordx2 v[140:141], v[64:65], off
	global_load_dwordx2 v[142:143], v[66:67], off
	v_mov_b64_e32 v[144:145], v[146:147]
	s_and_saveexec_b64 s[10:11], s[30:31]
	s_cbranch_execz .LBB0_614
	v_add_co_u32_e32 v64, vcc, 0x1e060000, v72
	s_nop 1
	v_addc_co_u32_e32 v65, vcc, 0, v73, vcc
	global_load_dwordx2 v[144:145], v[64:65], off
